# grid barrier spin loops: poll back-off s_sleep 8 instead of 2 (fewer coherent polls from idle CUs while tail tiles of a phase still run)
# baseline (speedup 1.0000x reference)
; DI void gbar(const Params& p, unsigned& target) {
;     ...
;     while (__hip_atomic_load(bar, __ATOMIC_RELAXED, __HIP_MEMORY_SCOPE_AGENT) < target) __builtin_amdgcn_s_sleep(2);
.LBB0_170:
	s_sleep 8
	global_load_dword v1, v0, s[4:5] sc1
	s_waitcnt vmcnt(0)
	v_cmp_gt_u32_e32 vcc, s97, v1
	s_cbranch_vccnz .LBB0_170

; DI void gbar(const Params& p, unsigned& target) {
;     ...
;     while (__hip_atomic_load(bar, __ATOMIC_RELAXED, __HIP_MEMORY_SCOPE_AGENT) < target) __builtin_amdgcn_s_sleep(2);
.LBB0_189:
	s_sleep 8
	global_load_dword v1, v0, s[4:5] sc1
	s_waitcnt vmcnt(0)
	v_cmp_gt_u32_e32 vcc, s10, v1
	s_cbranch_vccnz .LBB0_189

; DI void gbar(const Params& p, unsigned& target) {
;     ...
;     while (__hip_atomic_load(bar, __ATOMIC_RELAXED, __HIP_MEMORY_SCOPE_AGENT) < target) __builtin_amdgcn_s_sleep(2);
.LBB0_214:
	s_sleep 8
	global_load_dword v0, v1, s[2:3] sc1
	s_waitcnt vmcnt(0)
	v_cmp_gt_u32_e32 vcc, s38, v0
	s_cbranch_vccnz .LBB0_214

; DI void gbar(const Params& p, unsigned& target) {
;     ...
;     while (__hip_atomic_load(bar, __ATOMIC_RELAXED, __HIP_MEMORY_SCOPE_AGENT) < target) __builtin_amdgcn_s_sleep(2);
.LBB0_398:
	s_sleep 8
	global_load_dword v0, v1, s[2:3] sc1
	s_waitcnt vmcnt(0)
	v_cmp_gt_u32_e32 vcc, s8, v0
	s_cbranch_vccnz .LBB0_398

; DI void gbar(const Params& p, unsigned& target) {
;     ...
;     while (__hip_atomic_load(bar, __ATOMIC_RELAXED, __HIP_MEMORY_SCOPE_AGENT) < target) __builtin_amdgcn_s_sleep(2);
.LBB0_784:
	s_sleep 8
	global_load_dword v0, v1, s[2:3] sc1
	s_waitcnt vmcnt(0)
	v_cmp_gt_u32_e32 vcc, s34, v0
	s_cbranch_vccnz .LBB0_784

; DI void gbar(const Params& p, unsigned& target) {
;     ...
;     while (__hip_atomic_load(bar, __ATOMIC_RELAXED, __HIP_MEMORY_SCOPE_AGENT) < target) __builtin_amdgcn_s_sleep(2);
.LBB0_828:
	s_sleep 8
	global_load_dword v0, v1, s[2:3] sc1
	s_waitcnt vmcnt(0)
	v_cmp_gt_u32_e32 vcc, s13, v0
	s_cbranch_vccnz .LBB0_828

; DI void gbar(const Params& p, unsigned& target) {
;     ...
;     while (__hip_atomic_load(bar, __ATOMIC_RELAXED, __HIP_MEMORY_SCOPE_AGENT) < target) __builtin_amdgcn_s_sleep(2);
.LBB0_847:
	s_sleep 8
	global_load_dword v0, v1, s[2:3] sc1
	s_waitcnt vmcnt(0)
	v_cmp_gt_u32_e32 vcc, s29, v0
	s_cbranch_vccnz .LBB0_847

; DI void gbar(const Params& p, unsigned& target) {
;     ...
;     while (__hip_atomic_load(bar, __ATOMIC_RELAXED, __HIP_MEMORY_SCOPE_AGENT) < target) __builtin_amdgcn_s_sleep(2);
.LBB0_866:
	s_sleep 8
	global_load_dword v0, v1, s[2:3] sc1
	s_waitcnt vmcnt(0)
	v_cmp_gt_u32_e32 vcc, s26, v0
	s_cbranch_vccnz .LBB0_866

; DI void gbar(const Params& p, unsigned& target) {
;     ...
;     while (__hip_atomic_load(bar, __ATOMIC_RELAXED, __HIP_MEMORY_SCOPE_AGENT) < target) __builtin_amdgcn_s_sleep(2);
.LBB0_921:
	s_sleep 8
	global_load_dword v0, v1, s[2:3] sc1
	s_waitcnt vmcnt(0)
	v_cmp_gt_u32_e32 vcc, s26, v0
	s_cbranch_vccnz .LBB0_921
	s_branch .Ltramp_192
